# peeled first K-iteration waits with vmcnt(24) instead of vmcnt(8) for its first two waits when a hand-written epilogue (>=16 younger stores) preceded it, so the epilogue stores can drain under the fir
# speedup vs baseline: 1.0106x; 1.0106x over previous
;     __host__ __device__ __forceinline__ bool next(int i, Unit& uo) const {
;         if (ns == 8) {
;             const int L = i * G + c; Unit u;
;             if (L < 512) {
;                 int wgid = L; { const int q = 512 / NXCD, xcd = wgid % NXCD, off = wgid / NXCD; wgid = xcd * q + off; }
;                 const int nig = WGM * nN; const int gid = wgid / nig, fm = gid * WGM;
;                 u.pm = fm + ((wgid % nig) / nN); u.pn = (wgid % nig) % nN; u.kb = 0; u.nk = KT; u.part = 2;
;             } else {
;                 const int q = L - 512, t = q % 32, kp = q / 32;
;                 u.pm = 64 + t / 8; u.pn = t % 8; u.nk = KT / 8; u.kb = kp * u.nk; u.part = 16 + kp;
;             }
;             uo = u; return L < 768;
;         }
;         const int np = nwg * ns;
;         const int L = i * G + c; const bool ok = L < np;
;         int wgid = L; { const int q = np / NXCD, r = np % NXCD, xcd = wgid % NXCD, off = wgid / NXCD; wgid = (xcd < r ? xcd * (q + 1) : r * (q + 1) + (xcd - r) * q) + off; }
;         const int half = wgid >= nwg ? 1 : 0; wgid -= half * nwg;
;         const int nig = WGM * nN, gid = wgid / nig, fm = gid * WGM, gsz = (nM - fm) < WGM ? (nM - fm) : WGM;
;         Unit u; u.pm = fm + ((wgid % nig) % gsz); u.pn = (wgid % nig) / gsz; u.nk = KT / ns; u.kb = half * u.nk; u.part = ns == 2 ? half : 2;
; DI void run_gemm(LAS unsigned char* lds, const bf16* A, int lda, const bf16* Bt, int M, int N, int K, const EpiMode& E) {
;   pg8::Gemm g{A, Bt, M, N, K, lda}; pg8::StaticOrder S; S.init(M, N, K, (int)gridDim.x, (int)blockIdx.x, E.mode == EM_TAIL ? 8 : E.mode == EM_SPLIT ? 2 : 1);
.LBB0_452:
	s_and_b64 vcc, exec, s[6:7]
	s_cbranch_vccz .LBB0_944
	v_writelane_b32 v255, 0, 62
	s_cmp_lg_u32 s71, 6
	v_writelane_b32 v255, s22, 37
	s_cselect_b64 s[72:73], -1, 0
	s_cmp_eq_u32 s71, 5
	v_writelane_b32 v255, s23, 38
	s_cselect_b64 s[6:7], -1, 0
	s_and_b64 s[0:1], s[6:7], exec
	v_readlane_b32 s2, v255, 30
	s_cselect_b32 s0, 2, 1
	s_ashr_i32 s1, s2, 31
	s_lshr_b32 s1, s1, 24
	s_add_i32 s1, s2, s1
	v_readlane_b32 s2, v255, 29
	s_ashr_i32 s29, s1, 8
	s_ashr_i32 s1, s2, 31
	s_lshr_b32 s1, s1, 24
	s_add_i32 s1, s2, s1
	s_ashr_i32 s21, s20, 31
	s_ashr_i32 s4, s1, 8
	s_lshr_b32 s1, s21, 26
	s_add_i32 s1, s20, s1
	v_mov_b32_e32 v12, v181
	s_mul_i32 s28, s29, s4
	s_ashr_i32 s87, s1, 6
	s_mov_b64 s[8:9], -1
	v_readfirstlane_b32 s1, v12
	s_and_b64 vcc, exec, s[72:73]
	s_cbranch_vccz .LBB0_459
	v_cndmask_b32_e64 v0, 0, 1, s[6:7]
	s_nop 0
	v_readfirstlane_b32 s2, v0
	s_lshl_b32 s2, s28, s2
	s_ashr_i32 s3, s2, 31
	s_lshr_b32 s3, s3, 29
	s_add_i32 s3, s2, s3
	s_ashr_i32 s10, s3, 3
	s_and_b32 s3, s3, -8
	s_sub_i32 s11, s2, s3
	s_add_i32 s5, s10, 1
	s_cmp_ge_i32 s70, s11
	s_cbranch_scc0 .LBB0_456
	s_sub_i32 s8, s70, s11
	s_mul_i32 s3, s5, s11
	s_mul_i32 s8, s8, s10
	s_add_i32 s3, s8, s3
	s_mov_b64 s[8:9], 0

; #define PG8_STAGE(bufoff, gbase, voff) do { _Pragma("unroll") for (int _i = 0; _i < 2; ++_i) \
;         __builtin_amdgcn_global_load_lds((const unsigned*)((const char*)(gbase) + (voff)[_i]), (PG8_LAS unsigned*)(lds + (bufoff) + ldsw + _i * 8192), 16, 0, 0); } while (0)
; #define PG8_LDA(dst, b, h) do { _Pragma("unroll") for (int m = 0; m < 4; ++m) _Pragma("unroll") for (int k = 0; k < 2; ++k) dst[m][k] = *(const PG8_LAS bf16x8*)(lds + PG8_SA(b, h) + aoff + m * 2048 + k * 1024); } while (0)
; #define PG8_LDB(dst, b, h) do { _Pragma("unroll") for (int n = 0; n < 2; ++n) _Pragma("unroll") for (int k = 0; k < 2; ++k) dst[n][k] = *(const PG8_LAS bf16x8*)(lds + PG8_SB(b, h) + boff + n * 2048 + k * 1024); } while (0)
; #define PG8_MMA(ai, bj, At, Bt) do { __builtin_amdgcn_s_setprio(1); _Pragma("unroll") for (int m = 0; m < 4; ++m) _Pragma("unroll") for (int n = 0; n < 2; ++n) _Pragma("unroll") for (int k = 0; k < 2; ++k) \
;         acc[ai][bj][m][n] = __builtin_amdgcn_mfma_f32_16x16x32_bf16(Bt[n][k], At[m][k], acc[ai][bj][m][n], 0, 0, 0); __builtin_amdgcn_s_setprio(0); } while (0)
; #define PG8_WAIT_V(n) asm volatile("s_waitcnt vmcnt(" #n ")" ::: "memory")
; #define PG8_WAIT_L(n) asm volatile("s_waitcnt lgkmcnt(" #n ")" ::: "memory")
; #define PG8_BAR __builtin_amdgcn_s_barrier()
; #define PG8_SCHED __builtin_amdgcn_sched_barrier(0)
; template <class Epi, class Sched, bool ALIGN_EPI = false, bool SP2 = false>
; __device__ __forceinline__ void gemm_phase(PG8_LAS unsigned char* lds, const Gemm g, const Sched& S, const Epi& E) {
;     ...
;             PG8_LDB(B0, 0, 0); PG8_LDB(B1, 0, 1); PG8_SCHED; PG8_LDA(At, 0, 0); PG8_STAGE(PG8_SA(1, 1), a1 + hstepA, voffA);
;             PG8_WAIT_V(8); PG8_WAIT_L(0); PG8_BAR; PG8_MMA(0, 0, At, B0); PG8_MMA(0, 1, At, B1); PG8_BAR; PG8_SCHED;
.LBB0_486:
	v_readlane_b32 s99, v255, 62
	s_add_i32 s20, s62, -2
	s_add_u32 s44, s44, 0x80
	s_addc_u32 s45, s45, 0
	s_add_u32 s21, s46, 0x100
	s_addc_u32 s40, s47, 0
	s_mov_b32 s24, 0
	s_add_i32 s41, s24, 2
	s_add_u32 s22, s44, 0x80
	s_addc_u32 s23, s45, 0
	s_add_i32 s48, 0, 0x10000
	s_cmp_eq_u32 s20, s24
	s_cselect_b32 s25, s75, s23
	s_cselect_b32 s24, s74, s22
	v_add_u32_e32 v112, s48, v176
	s_cselect_b32 s47, s69, s40
	s_cselect_b32 s46, s68, s21
	s_add_i32 s22, 0, 0x14000
	ds_read_b128 v[130:133], v112
	ds_read_b128 v[134:137], v112 offset:1024
	ds_read_b128 v[138:141], v112 offset:2048
	ds_read_b128 v[154:157], v112 offset:3072
	v_add_u32_e32 v112, s22, v176
	ds_read_b128 v[158:161], v112
	ds_read_b128 v[162:165], v112 offset:1024
	ds_read_b128 v[166:169], v112 offset:2048
	ds_read_b128 v[170:173], v112 offset:3072
	v_lshl_add_u64 v[174:175], s[44:45], 0, v[150:151]
	s_add_i32 m0, s33, 0xc000
	ds_read_b128 v[188:191], v177
	ds_read_b128 v[192:195], v177 offset:1024
	ds_read_b128 v[196:199], v177 offset:2048
	ds_read_b128 v[200:203], v177 offset:3072
	ds_read_b128 v[204:207], v177 offset:4096
	ds_read_b128 v[216:219], v177 offset:5120
	ds_read_b128 v[220:223], v177 offset:6144
	ds_read_b128 v[224:227], v177 offset:7168
	global_load_lds_dwordx4 v[174:175], off
	v_lshl_add_u64 v[174:175], s[44:45], 0, v[152:153]
	s_add_i32 m0, s33, 0xe000
	s_nop 0
	global_load_lds_dwordx4 v[174:175], off
	s_cmp_eq_u32 s99, 0
	s_cbranch_scc1 .Lpw0_strict
	s_waitcnt vmcnt(24)
	s_branch .Lpw0_done

; #define PG8_STAGE(bufoff, gbase, voff) do { _Pragma("unroll") for (int _i = 0; _i < 2; ++_i) \
;         __builtin_amdgcn_global_load_lds((const unsigned*)((const char*)(gbase) + (voff)[_i]), (PG8_LAS unsigned*)(lds + (bufoff) + ldsw + _i * 8192), 16, 0, 0); } while (0)
; #define PG8_LDA(dst, b, h) do { _Pragma("unroll") for (int m = 0; m < 4; ++m) _Pragma("unroll") for (int k = 0; k < 2; ++k) dst[m][k] = *(const PG8_LAS bf16x8*)(lds + PG8_SA(b, h) + aoff + m * 2048 + k * 1024); } while (0)
; #define PG8_MMA(ai, bj, At, Bt) do { __builtin_amdgcn_s_setprio(1); _Pragma("unroll") for (int m = 0; m < 4; ++m) _Pragma("unroll") for (int n = 0; n < 2; ++n) _Pragma("unroll") for (int k = 0; k < 2; ++k) \
;         acc[ai][bj][m][n] = __builtin_amdgcn_mfma_f32_16x16x32_bf16(Bt[n][k], At[m][k], acc[ai][bj][m][n], 0, 0, 0); __builtin_amdgcn_s_setprio(0); } while (0)
; #define PG8_WAIT_V(n) asm volatile("s_waitcnt vmcnt(" #n ")" ::: "memory")
; #define PG8_WAIT_L(n) asm volatile("s_waitcnt lgkmcnt(" #n ")" ::: "memory")
; #define PG8_BAR __builtin_amdgcn_s_barrier()
; #define PG8_SCHED __builtin_amdgcn_sched_barrier(0)
; template <class Epi, class Sched, bool ALIGN_EPI = false, bool SP2 = false>
; __device__ __forceinline__ void gemm_phase(PG8_LAS unsigned char* lds, const Gemm g, const Sched& S, const Epi& E) {
;     ...
;             PG8_WAIT_V(8); PG8_WAIT_L(0); PG8_BAR; PG8_MMA(0, 0, At, B0); PG8_MMA(0, 1, At, B1); PG8_BAR; PG8_SCHED;
;             PG8_LDA(At, 0, 1); PG8_STAGE(PG8_SB(0, 0), b2, voffB); PG8_STAGE(PG8_SB(0, 1), b2 + hstep, voffB); PG8_STAGE(PG8_SA(0, 0), a2, voffA);
;             PG8_WAIT_V(8); PG8_WAIT_L(0); PG8_BAR; PG8_MMA(1, 0, At, B0); PG8_MMA(1, 1, At, B1); PG8_BAR; PG8_SCHED;
.Lpw0_done:
	s_waitcnt lgkmcnt(0)
	s_barrier
	s_setprio 1
	s_waitcnt lgkmcnt(0)
	v_mfma_f32_16x16x32_bf16 v[126:129], v[130:133], v[188:191], 0
	v_mfma_f32_16x16x32_bf16 v[122:125], v[138:141], v[188:191], 0
	v_mfma_f32_16x16x32_bf16 v[108:111], v[130:133], v[196:199], 0
	v_mfma_f32_16x16x32_bf16 v[104:107], v[138:141], v[196:199], 0
	v_mfma_f32_16x16x32_bf16 v[92:95], v[130:133], v[204:207], 0
	v_mfma_f32_16x16x32_bf16 v[88:91], v[138:141], v[204:207], 0
	v_mfma_f32_16x16x32_bf16 v[76:79], v[130:133], v[220:223], 0
	v_mfma_f32_16x16x32_bf16 v[72:75], v[138:141], v[220:223], 0
	v_mfma_f32_16x16x32_bf16 v[126:129], v[134:137], v[192:195], v[126:129]
	v_mfma_f32_16x16x32_bf16 v[122:125], v[154:157], v[192:195], v[122:125]
	v_mfma_f32_16x16x32_bf16 v[108:111], v[134:137], v[200:203], v[108:111]
	v_mfma_f32_16x16x32_bf16 v[104:107], v[154:157], v[200:203], v[104:107]
	v_mfma_f32_16x16x32_bf16 v[92:95], v[134:137], v[216:219], v[92:95]
	v_mfma_f32_16x16x32_bf16 v[88:91], v[154:157], v[216:219], v[88:91]
	v_mfma_f32_16x16x32_bf16 v[76:79], v[134:137], v[224:227], v[76:79]
	v_mfma_f32_16x16x32_bf16 v[72:75], v[154:157], v[224:227], v[72:75]
	s_setprio 0
	s_setprio 1
	v_mfma_f32_16x16x32_bf16 v[118:121], v[158:161], v[188:191], 0
	v_mfma_f32_16x16x32_bf16 v[114:117], v[166:169], v[188:191], 0
	v_mfma_f32_16x16x32_bf16 v[100:103], v[158:161], v[196:199], 0
	v_mfma_f32_16x16x32_bf16 v[96:99], v[166:169], v[196:199], 0
	v_mfma_f32_16x16x32_bf16 v[84:87], v[158:161], v[204:207], 0
	v_mfma_f32_16x16x32_bf16 v[80:83], v[166:169], v[204:207], 0
	v_mfma_f32_16x16x32_bf16 v[68:71], v[158:161], v[220:223], 0
	v_mfma_f32_16x16x32_bf16 v[64:67], v[166:169], v[220:223], 0
	v_mfma_f32_16x16x32_bf16 v[118:121], v[162:165], v[192:195], v[118:121]
	v_mfma_f32_16x16x32_bf16 v[114:117], v[170:173], v[192:195], v[114:117]
	v_mfma_f32_16x16x32_bf16 v[100:103], v[162:165], v[200:203], v[100:103]
	v_mfma_f32_16x16x32_bf16 v[96:99], v[170:173], v[200:203], v[96:99]
	v_mfma_f32_16x16x32_bf16 v[84:87], v[162:165], v[216:219], v[84:87]
	v_mfma_f32_16x16x32_bf16 v[80:83], v[170:173], v[216:219], v[80:83]
	v_mfma_f32_16x16x32_bf16 v[68:71], v[162:165], v[224:227], v[68:71]
	v_mfma_f32_16x16x32_bf16 v[64:67], v[170:173], v[224:227], v[64:67]
	s_setprio 0
	s_barrier
	s_add_i32 s23, s48, s39
	v_lshl_add_u64 v[174:175], s[46:47], 0, v[144:145]
	s_mov_b32 m0, s23
	ds_read_b128 v[188:191], v177 offset:16384
	ds_read_b128 v[192:195], v177 offset:17408
	ds_read_b128 v[196:199], v177 offset:18432
	ds_read_b128 v[200:203], v177 offset:19456
	ds_read_b128 v[204:207], v177 offset:20480
	ds_read_b128 v[216:219], v177 offset:21504
	ds_read_b128 v[220:223], v177 offset:22528
	ds_read_b128 v[224:227], v177 offset:23552
	global_load_lds_dwordx4 v[174:175], off
	s_add_i32 m0, s23, 0x2000
	v_lshl_add_u64 v[178:179], s[46:47], 0, v[148:149]
	s_add_u32 s46, s46, s8
	s_addc_u32 s47, s47, s9
	s_add_i32 s22, s22, s39
	global_load_lds_dwordx4 v[178:179], off
	v_lshl_add_u64 v[212:213], s[46:47], 0, v[144:145]
	s_mov_b32 m0, s22
	v_lshl_add_u64 v[214:215], s[46:47], 0, v[148:149]
	global_load_lds_dwordx4 v[212:213], off
	s_add_i32 m0, s22, 0x2000
	v_lshl_add_u64 v[228:229], s[24:25], 0, v[142:143]
	global_load_lds_dwordx4 v[214:215], off
	s_mov_b32 m0, s33
	v_lshl_add_u64 v[230:231], s[24:25], 0, v[146:147]
	global_load_lds_dwordx4 v[228:229], off
	s_mov_b32 m0, s37
	s_nop 0
	global_load_lds_dwordx4 v[230:231], off
	s_cmp_eq_u32 s99, 0
	s_cbranch_scc1 .Lpw1_strict
	s_waitcnt vmcnt(24)
	s_branch .Lpw1_done

; #define PG8_STAGE(bufoff, gbase, voff) do { _Pragma("unroll") for (int _i = 0; _i < 2; ++_i) \
;         __builtin_amdgcn_global_load_lds((const unsigned*)((const char*)(gbase) + (voff)[_i]), (PG8_LAS unsigned*)(lds + (bufoff) + ldsw + _i * 8192), 16, 0, 0); } while (0)
; #define PG8_LDA(dst, b, h) do { _Pragma("unroll") for (int m = 0; m < 4; ++m) _Pragma("unroll") for (int k = 0; k < 2; ++k) dst[m][k] = *(const PG8_LAS bf16x8*)(lds + PG8_SA(b, h) + aoff + m * 2048 + k * 1024); } while (0)
; #define PG8_LDB(dst, b, h) do { _Pragma("unroll") for (int n = 0; n < 2; ++n) _Pragma("unroll") for (int k = 0; k < 2; ++k) dst[n][k] = *(const PG8_LAS bf16x8*)(lds + PG8_SB(b, h) + boff + n * 2048 + k * 1024); } while (0)
; #define PG8_MMA(ai, bj, At, Bt) do { __builtin_amdgcn_s_setprio(1); _Pragma("unroll") for (int m = 0; m < 4; ++m) _Pragma("unroll") for (int n = 0; n < 2; ++n) _Pragma("unroll") for (int k = 0; k < 2; ++k) \
;         acc[ai][bj][m][n] = __builtin_amdgcn_mfma_f32_16x16x32_bf16(Bt[n][k], At[m][k], acc[ai][bj][m][n], 0, 0, 0); __builtin_amdgcn_s_setprio(0); } while (0)
; #define PG8_WAIT_V(n) asm volatile("s_waitcnt vmcnt(" #n ")" ::: "memory")
; #define PG8_WAIT_L(n) asm volatile("s_waitcnt lgkmcnt(" #n ")" ::: "memory")
; #define PG8_BAR __builtin_amdgcn_s_barrier()
; #define PG8_SCHED __builtin_amdgcn_sched_barrier(0)
; template <class Epi, class Sched, bool ALIGN_EPI = false, bool SP2 = false>
; __device__ __forceinline__ void gemm_phase(PG8_LAS unsigned char* lds, const Gemm g, const Sched& S, const Epi& E) {
;     ...
;             PG8_WAIT_V(8); PG8_WAIT_L(0); PG8_BAR; PG8_MMA(1, 0, At, B0); PG8_MMA(1, 1, At, B1); PG8_BAR; PG8_SCHED;
;             PG8_LDB(B0, 1, 0); PG8_LDB(B1, 1, 1); PG8_SCHED; PG8_LDA(At, 1, 0); PG8_STAGE(PG8_SA(0, 1), a2 + hstepA, voffA);
;             PG8_WAIT_V(8); PG8_WAIT_L(0); PG8_BAR; PG8_MMA(0, 0, At, B0); PG8_MMA(0, 1, At, B1); PG8_BAR; PG8_SCHED;
.Lpw1_done:
	s_waitcnt lgkmcnt(0)
	s_barrier
	s_setprio 1
	s_waitcnt lgkmcnt(0)
	v_mfma_f32_16x16x32_bf16 v[60:63], v[130:133], v[188:191], 0
	v_mfma_f32_16x16x32_bf16 v[56:59], v[138:141], v[188:191], 0
	v_mfma_f32_16x16x32_bf16 v[44:47], v[130:133], v[196:199], 0
	v_mfma_f32_16x16x32_bf16 v[40:43], v[138:141], v[196:199], 0
	v_mfma_f32_16x16x32_bf16 v[28:31], v[130:133], v[204:207], 0
	v_mfma_f32_16x16x32_bf16 v[24:27], v[138:141], v[204:207], 0
	v_mfma_f32_16x16x32_bf16 v[12:15], v[130:133], v[220:223], 0
	v_mfma_f32_16x16x32_bf16 v[8:11], v[138:141], v[220:223], 0
	v_mfma_f32_16x16x32_bf16 v[60:63], v[134:137], v[192:195], v[60:63]
	v_mfma_f32_16x16x32_bf16 v[56:59], v[154:157], v[192:195], v[56:59]
	v_mfma_f32_16x16x32_bf16 v[44:47], v[134:137], v[200:203], v[44:47]
	v_mfma_f32_16x16x32_bf16 v[40:43], v[154:157], v[200:203], v[40:43]
	v_mfma_f32_16x16x32_bf16 v[28:31], v[134:137], v[216:219], v[28:31]
	v_mfma_f32_16x16x32_bf16 v[24:27], v[154:157], v[216:219], v[24:27]
	v_mfma_f32_16x16x32_bf16 v[12:15], v[134:137], v[224:227], v[12:15]
	v_mfma_f32_16x16x32_bf16 v[8:11], v[154:157], v[224:227], v[8:11]
	s_setprio 0
	s_setprio 1
	v_mfma_f32_16x16x32_bf16 v[52:55], v[158:161], v[188:191], 0
	v_mfma_f32_16x16x32_bf16 v[48:51], v[166:169], v[188:191], 0
	v_mfma_f32_16x16x32_bf16 v[36:39], v[158:161], v[196:199], 0
	v_mfma_f32_16x16x32_bf16 v[32:35], v[166:169], v[196:199], 0
	v_mfma_f32_16x16x32_bf16 v[20:23], v[158:161], v[204:207], 0
	v_mfma_f32_16x16x32_bf16 v[16:19], v[166:169], v[204:207], 0
	v_mfma_f32_16x16x32_bf16 v[4:7], v[158:161], v[220:223], 0
	v_mfma_f32_16x16x32_bf16 v[0:3], v[166:169], v[220:223], 0
	v_mfma_f32_16x16x32_bf16 v[52:55], v[162:165], v[192:195], v[52:55]
	v_mfma_f32_16x16x32_bf16 v[48:51], v[170:173], v[192:195], v[48:51]
	v_mfma_f32_16x16x32_bf16 v[36:39], v[162:165], v[200:203], v[36:39]
	v_mfma_f32_16x16x32_bf16 v[32:35], v[170:173], v[200:203], v[32:35]
	v_mfma_f32_16x16x32_bf16 v[20:23], v[162:165], v[216:219], v[20:23]
	v_mfma_f32_16x16x32_bf16 v[16:19], v[170:173], v[216:219], v[16:19]
	v_mfma_f32_16x16x32_bf16 v[4:7], v[162:165], v[224:227], v[4:7]
	v_mfma_f32_16x16x32_bf16 v[0:3], v[170:173], v[224:227], v[0:3]
	s_setprio 0
	s_barrier
	s_add_i32 s22, 0, 0x18000
	v_add_u32_e32 v112, s22, v176
	s_add_i32 s23, 0, 0x1c000
	ds_read_b128 v[130:133], v112
	ds_read_b128 v[134:137], v112 offset:1024
	ds_read_b128 v[138:141], v112 offset:2048
	ds_read_b128 v[154:157], v112 offset:3072
	v_add_u32_e32 v112, s23, v176
	ds_read_b128 v[158:161], v112
	ds_read_b128 v[162:165], v112 offset:1024
	ds_read_b128 v[166:169], v112 offset:2048
	ds_read_b128 v[170:173], v112 offset:3072
	s_add_u32 s24, s24, s12
	s_addc_u32 s25, s25, s13
	s_mov_b32 m0, s50
	v_lshl_add_u64 v[232:233], s[24:25], 0, v[142:143]
	ds_read_b128 v[188:191], v177 offset:32768
	ds_read_b128 v[192:195], v177 offset:33792
	ds_read_b128 v[196:199], v177 offset:34816
	ds_read_b128 v[200:203], v177 offset:35840
	ds_read_b128 v[204:207], v177 offset:36864
	ds_read_b128 v[216:219], v177 offset:37888
	ds_read_b128 v[220:223], v177 offset:38912
	ds_read_b128 v[224:227], v177 offset:39936
	global_load_lds_dwordx4 v[232:233], off
	v_lshl_add_u64 v[232:233], s[24:25], 0, v[146:147]
	s_mov_b32 m0, s51
	s_nop 0
	global_load_lds_dwordx4 v[232:233], off
	s_waitcnt vmcnt(8)
	s_waitcnt lgkmcnt(0)
	s_barrier
	s_setprio 1
	s_waitcnt lgkmcnt(0)
	v_mfma_f32_16x16x32_bf16 v[126:129], v[130:133], v[188:191], v[126:129]
	v_mfma_f32_16x16x32_bf16 v[122:125], v[138:141], v[188:191], v[122:125]
	v_mfma_f32_16x16x32_bf16 v[108:111], v[130:133], v[196:199], v[108:111]
	v_mfma_f32_16x16x32_bf16 v[104:107], v[138:141], v[196:199], v[104:107]
	v_mfma_f32_16x16x32_bf16 v[92:95], v[130:133], v[204:207], v[92:95]
	v_mfma_f32_16x16x32_bf16 v[88:91], v[138:141], v[204:207], v[88:91]
	v_mfma_f32_16x16x32_bf16 v[76:79], v[130:133], v[220:223], v[76:79]
	v_mfma_f32_16x16x32_bf16 v[72:75], v[138:141], v[220:223], v[72:75]
	v_mfma_f32_16x16x32_bf16 v[126:129], v[134:137], v[192:195], v[126:129]
	v_mfma_f32_16x16x32_bf16 v[122:125], v[154:157], v[192:195], v[122:125]
	v_mfma_f32_16x16x32_bf16 v[108:111], v[134:137], v[200:203], v[108:111]
	v_mfma_f32_16x16x32_bf16 v[104:107], v[154:157], v[200:203], v[104:107]
	v_mfma_f32_16x16x32_bf16 v[92:95], v[134:137], v[216:219], v[92:95]
	v_mfma_f32_16x16x32_bf16 v[88:91], v[154:157], v[216:219], v[88:91]
	v_mfma_f32_16x16x32_bf16 v[76:79], v[134:137], v[224:227], v[76:79]
	v_mfma_f32_16x16x32_bf16 v[72:75], v[154:157], v[224:227], v[72:75]
	s_setprio 0
	s_setprio 1
	v_mfma_f32_16x16x32_bf16 v[118:121], v[158:161], v[188:191], v[118:121]
	v_mfma_f32_16x16x32_bf16 v[114:117], v[166:169], v[188:191], v[114:117]
	v_mfma_f32_16x16x32_bf16 v[100:103], v[158:161], v[196:199], v[100:103]
	v_mfma_f32_16x16x32_bf16 v[96:99], v[166:169], v[196:199], v[96:99]
	v_mfma_f32_16x16x32_bf16 v[84:87], v[158:161], v[204:207], v[84:87]
	v_mfma_f32_16x16x32_bf16 v[80:83], v[166:169], v[204:207], v[80:83]
	v_mfma_f32_16x16x32_bf16 v[68:71], v[158:161], v[220:223], v[68:71]
	v_mfma_f32_16x16x32_bf16 v[64:67], v[166:169], v[220:223], v[64:67]
	v_mfma_f32_16x16x32_bf16 v[118:121], v[162:165], v[192:195], v[118:121]
	v_mfma_f32_16x16x32_bf16 v[114:117], v[170:173], v[192:195], v[114:117]
	v_mfma_f32_16x16x32_bf16 v[100:103], v[162:165], v[200:203], v[100:103]
	v_mfma_f32_16x16x32_bf16 v[96:99], v[170:173], v[200:203], v[96:99]
	v_mfma_f32_16x16x32_bf16 v[84:87], v[162:165], v[216:219], v[84:87]
	v_mfma_f32_16x16x32_bf16 v[80:83], v[170:173], v[216:219], v[80:83]
	v_mfma_f32_16x16x32_bf16 v[68:71], v[162:165], v[224:227], v[68:71]
	v_mfma_f32_16x16x32_bf16 v[64:67], v[170:173], v[224:227], v[64:67]
	s_setprio 0
	s_barrier
; #define PG8_STAGE(bufoff, gbase, voff) do { _Pragma("unroll") for (int _i = 0; _i < 2; ++_i) \
;         __builtin_amdgcn_global_load_lds((const unsigned*)((const char*)(gbase) + (voff)[_i]), (PG8_LAS unsigned*)(lds + (bufoff) + ldsw + _i * 8192), 16, 0, 0); } while (0)
; #define PG8_LDA(dst, b, h) do { _Pragma("unroll") for (int m = 0; m < 4; ++m) _Pragma("unroll") for (int k = 0; k < 2; ++k) dst[m][k] = *(const PG8_LAS bf16x8*)(lds + PG8_SA(b, h) + aoff + m * 2048 + k * 1024); } while (0)
; #define PG8_MMA(ai, bj, At, Bt) do { __builtin_amdgcn_s_setprio(1); _Pragma("unroll") for (int m = 0; m < 4; ++m) _Pragma("unroll") for (int n = 0; n < 2; ++n) _Pragma("unroll") for (int k = 0; k < 2; ++k) \
;         acc[ai][bj][m][n] = __builtin_amdgcn_mfma_f32_16x16x32_bf16(Bt[n][k], At[m][k], acc[ai][bj][m][n], 0, 0, 0); __builtin_amdgcn_s_setprio(0); } while (0)
; #define PG8_WAIT_V(n) asm volatile("s_waitcnt vmcnt(" #n ")" ::: "memory")
; #define PG8_WAIT_L(n) asm volatile("s_waitcnt lgkmcnt(" #n ")" ::: "memory")
; #define PG8_BAR __builtin_amdgcn_s_barrier()
; #define PG8_SCHED __builtin_amdgcn_sched_barrier(0)
; template <class Epi, class Sched, bool ALIGN_EPI = false, bool SP2 = false>
; __device__ __forceinline__ void gemm_phase(PG8_LAS unsigned char* lds, const Gemm g, const Sched& S, const Epi& E) {
;     ...
;             PG8_LDA(At, 1, 1); PG8_STAGE(PG8_SB(1, 0), b3, voffB); PG8_STAGE(PG8_SB(1, 1), b3 + hstep, voffB); PG8_STAGE(PG8_SA(1, 0), a3, voffA);
;             PG8_WAIT_V(8); PG8_WAIT_L(0); PG8_BAR; PG8_MMA(1, 0, At, B0); PG8_MMA(1, 1, At, B1); PG8_BAR; PG8_SCHED;
	s_add_i32 s22, s22, s39
	v_lshl_add_u64 v[174:175], v[174:175], 0, s[30:31]
	s_mov_b32 m0, s22
	ds_read_b128 v[188:191], v177 offset:49152
	ds_read_b128 v[192:195], v177 offset:50176
	ds_read_b128 v[196:199], v177 offset:51200
	ds_read_b128 v[200:203], v177 offset:52224
	ds_read_b128 v[204:207], v177 offset:53248
	ds_read_b128 v[216:219], v177 offset:54272
	ds_read_b128 v[220:223], v177 offset:55296
	ds_read_b128 v[224:227], v177 offset:56320
	global_load_lds_dwordx4 v[174:175], off
	v_lshl_add_u64 v[174:175], v[178:179], 0, s[30:31]
	s_add_i32 m0, s22, 0x2000
	s_add_i32 s22, s23, s39
	global_load_lds_dwordx4 v[174:175], off
	v_lshl_add_u64 v[174:175], v[212:213], 0, s[30:31]
	s_mov_b32 m0, s22
	s_nop 0
	global_load_lds_dwordx4 v[174:175], off
	v_lshl_add_u64 v[174:175], v[214:215], 0, s[30:31]
	s_add_i32 m0, s22, 0x2000
	s_nop 0
	global_load_lds_dwordx4 v[174:175], off
	v_lshl_add_u64 v[174:175], v[228:229], 0, s[30:31]
	s_mov_b32 m0, s57
	s_nop 0
	global_load_lds_dwordx4 v[174:175], off
	v_lshl_add_u64 v[174:175], v[230:231], 0, s[30:31]
	s_mov_b32 m0, s58
	s_nop 0
	global_load_lds_dwordx4 v[174:175], off
	s_waitcnt vmcnt(8)
	s_waitcnt lgkmcnt(0)
	s_barrier
	s_setprio 1
	s_waitcnt lgkmcnt(0)
	v_mfma_f32_16x16x32_bf16 v[60:63], v[130:133], v[188:191], v[60:63]
	v_mfma_f32_16x16x32_bf16 v[56:59], v[138:141], v[188:191], v[56:59]
	v_mfma_f32_16x16x32_bf16 v[44:47], v[130:133], v[196:199], v[44:47]
	v_mfma_f32_16x16x32_bf16 v[40:43], v[138:141], v[196:199], v[40:43]
	v_mfma_f32_16x16x32_bf16 v[28:31], v[130:133], v[204:207], v[28:31]
	v_mfma_f32_16x16x32_bf16 v[24:27], v[138:141], v[204:207], v[24:27]
	v_mfma_f32_16x16x32_bf16 v[12:15], v[130:133], v[220:223], v[12:15]
	v_mfma_f32_16x16x32_bf16 v[8:11], v[138:141], v[220:223], v[8:11]
	v_mfma_f32_16x16x32_bf16 v[60:63], v[134:137], v[192:195], v[60:63]
	v_mfma_f32_16x16x32_bf16 v[56:59], v[154:157], v[192:195], v[56:59]
	v_mfma_f32_16x16x32_bf16 v[44:47], v[134:137], v[200:203], v[44:47]
	v_mfma_f32_16x16x32_bf16 v[40:43], v[154:157], v[200:203], v[40:43]
	v_mfma_f32_16x16x32_bf16 v[28:31], v[134:137], v[216:219], v[28:31]
	v_mfma_f32_16x16x32_bf16 v[24:27], v[154:157], v[216:219], v[24:27]
	v_mfma_f32_16x16x32_bf16 v[12:15], v[134:137], v[224:227], v[12:15]
	v_mfma_f32_16x16x32_bf16 v[8:11], v[154:157], v[224:227], v[8:11]
	s_setprio 0
	s_setprio 1
	v_mfma_f32_16x16x32_bf16 v[52:55], v[158:161], v[188:191], v[52:55]
	v_mfma_f32_16x16x32_bf16 v[48:51], v[166:169], v[188:191], v[48:51]
	v_mfma_f32_16x16x32_bf16 v[36:39], v[158:161], v[196:199], v[36:39]
	v_mfma_f32_16x16x32_bf16 v[32:35], v[166:169], v[196:199], v[32:35]
	v_mfma_f32_16x16x32_bf16 v[20:23], v[158:161], v[204:207], v[20:23]
	v_mfma_f32_16x16x32_bf16 v[16:19], v[166:169], v[204:207], v[16:19]
	v_mfma_f32_16x16x32_bf16 v[4:7], v[158:161], v[220:223], v[4:7]
	v_mfma_f32_16x16x32_bf16 v[0:3], v[166:169], v[220:223], v[0:3]
	v_mfma_f32_16x16x32_bf16 v[52:55], v[162:165], v[192:195], v[52:55]
	v_mfma_f32_16x16x32_bf16 v[48:51], v[170:173], v[192:195], v[48:51]
	v_mfma_f32_16x16x32_bf16 v[36:39], v[162:165], v[200:203], v[36:39]
	v_mfma_f32_16x16x32_bf16 v[32:35], v[170:173], v[200:203], v[32:35]
	v_mfma_f32_16x16x32_bf16 v[20:23], v[162:165], v[216:219], v[20:23]
	v_mfma_f32_16x16x32_bf16 v[16:19], v[170:173], v[216:219], v[16:19]
	v_mfma_f32_16x16x32_bf16 v[4:7], v[162:165], v[224:227], v[4:7]
	v_mfma_f32_16x16x32_bf16 v[0:3], v[170:173], v[224:227], v[0:3]
	s_setprio 0
	s_barrier
	s_add_u32 s44, s44, 0x100
	s_addc_u32 s45, s45, 0
	s_add_u32 s21, s21, 0x100
	s_addc_u32 s40, s40, 0
	s_cmp_ge_i32 s41, s62
	s_mov_b32 s24, s41
	s_cbranch_scc1 .Lk_exit

;   DI void operator()(const f32x4 (&acc)[2][2][4][2], const pg8::Unit& u, int wr, int wc, int fr, int fq) const {
;     { int t_ = threadIdx.x; asm volatile("" : "+v"(t_)); fr = t_ & 15; fq = (t_ >> 4) & 3; }
;     switch (mode) {
;       case EM_BF16: run<EM_BF16>(acc, u, wr, wc, fr, fq); break;
;       case EM_RELU2: run<EM_RELU2>(acc, u, wr, wc, fr, fq); break;
;       case EM_F32: run<EM_F32>(acc, u, wr, wc, fr, fq); break;
;       case EM_QKV: run<EM_QKV>(acc, u, wr, wc, fr, fq); break;
;       case EM_SPLIT: run<EM_SPLIT>(acc, u, wr, wc, fr, fq); break;
;       case EM_TAIL: run<EM_TAIL>(acc, u, wr, wc, fr, fq); break;
;       default: run<EM_QROPE>(acc, u, wr, wc, fr, fq); break;
;     }
.LBB0_490:
	v_writelane_b32 v255, 0, 62
	v_mov_b32_e32 v112, v181
	s_cmp_lt_i32 s71, 3
	v_and_b32_e32 v179, 15, v112
	v_bfe_u32 v178, v112, 4, 2
	s_cmp_eq_u32 s71, 2
	s_cbranch_scc1 .Lepi_relu2
	s_cmp_eq_u32 s71, 0
	s_cbranch_scc1 .Lepi_plain
	s_cmp_eq_u32 s71, 6
	s_cbranch_scc1 .Lepi_plain
	s_cmp_lt_i32 s71, 3
	s_mov_b64 s[20:21], -1
	s_cbranch_scc1 .LBB0_668
	s_mov_b64 s[46:47], 0
	s_cmp_lt_i32 s71, 5
	s_mov_b64 s[48:49], 0
	s_cbranch_scc1 .LBB0_631
	s_cmp_gt_i32 s71, 5
	s_cbranch_scc0 .LBB0_560
	s_cmp_eq_u32 s71, 6
	s_mov_b64 s[48:49], -1
	s_cbranch_scc0 .LBB0_559
	s_lshl_b32 s40, s83, 8
	v_or_b32_e32 v112, s78, v179
	s_cmp_lt_u32 s64, 16
	v_add_u32_e32 v136, s40, v112
	s_cselect_b64 s[24:25], -1, 0
	v_ashrrev_i32_e32 v137, 31, v136
	s_and_b64 vcc, exec, s[24:25]
	s_cbranch_vccz .LBB0_496
	v_mul_lo_u32 v138, s89, v136
	v_mul_lo_u32 v139, s88, v137
	v_mad_u64_u32 v[134:135], s[20:21], s88, v136, 0
	v_add3_u32 v135, v135, v139, v138
	v_cvt_pk_bf16_f32 v130, v126, v127
	v_cvt_pk_bf16_f32 v131, v128, v129
	v_cvt_pk_bf16_f32 v132, v122, v123
	v_cvt_pk_bf16_f32 v133, v124, v125
	v_lshl_add_u64 v[140:141], v[134:135], 1, s[90:91]
	s_mov_b64 s[20:21], 0

; DI u32x4 pack8(f32x4 a, f32x4 b) { u32x4 w; w.x = cvtpk(a.x, a.y); w.y = cvtpk(a.z, a.w); w.z = cvtpk(b.x, b.y); w.w = cvtpk(b.z, b.w); return w; }
;   template <int MODE> DI void store8(int row, int col, f32x4 v0, f32x4 v1, int part) const {
;     if (MODE == EM_QKV || MODE == EM_RELU2 || MODE == EM_F32) { const float r_ = rs[row]; v0 *= r_; v1 *= r_; }
;     if (MODE == EM_TAIL) {
;       if (part >= 16) *(u32x4*)(O2 + ((size_t)(part - 16) * 1024 + (row - NPR)) * 2048 + col) = pack8(v0, v1);
;       else *(u32x4*)(O + (size_t)row * ldc + col) = pack8(v0, v1);
;     } else if (MODE == EM_SPLIT) {
;       bf16* d = (part & 1) ? O2 : O; *(u32x4*)(d + (size_t)row * ldc + col) = pack8(v0, v1);
;       if (part & 2) *(u32x4*)(O2 + (size_t)row * ldc + col) = (u32x4){0u, 0u, 0u, 0u};
;     } else if (MODE == EM_BF16) { *(u32x4*)(O + (size_t)row * ldc + col) = pack8(v0, v1); }
;     else if (MODE == EM_RELU2) {
;       f32x4 a = __builtin_elementwise_max(v0, (f32x4){0.f, 0.f, 0.f, 0.f}), b = __builtin_elementwise_max(v1, (f32x4){0.f, 0.f, 0.f, 0.f});
;       *(u32x4*)(O + (size_t)row * ldc + col) = pack8(a * a, b * b); }
.Lepi_plain_bd:
	v_cvt_pk_bf16_f32 v126, v126, v127
	v_cvt_pk_bf16_f32 v127, v128, v129
	v_cvt_pk_bf16_f32 v128, v122, v123
	v_cvt_pk_bf16_f32 v129, v124, v125
	global_store_dwordx4 v132, v[126:129], s[98:99]
	v_cvt_pk_bf16_f32 v118, v118, v119
	v_cvt_pk_bf16_f32 v119, v120, v121
	v_cvt_pk_bf16_f32 v120, v114, v115
	v_cvt_pk_bf16_f32 v121, v116, v117
	global_store_dwordx4 v132, v[118:121], s[98:99] offset:256
	v_add_u32_e32 v132, s20, v132
	v_cvt_pk_bf16_f32 v108, v108, v109
	v_cvt_pk_bf16_f32 v109, v110, v111
	v_cvt_pk_bf16_f32 v110, v104, v105
	v_cvt_pk_bf16_f32 v111, v106, v107
	global_store_dwordx4 v132, v[108:111], s[98:99]
	v_cvt_pk_bf16_f32 v100, v100, v101
	v_cvt_pk_bf16_f32 v101, v102, v103
	v_cvt_pk_bf16_f32 v102, v96, v97
	v_cvt_pk_bf16_f32 v103, v98, v99
	global_store_dwordx4 v132, v[100:103], s[98:99] offset:256
	v_add_u32_e32 v132, s20, v132
	v_cvt_pk_bf16_f32 v92, v92, v93
	v_cvt_pk_bf16_f32 v93, v94, v95
	v_cvt_pk_bf16_f32 v94, v88, v89
	v_cvt_pk_bf16_f32 v95, v90, v91
	global_store_dwordx4 v132, v[92:95], s[98:99]
	v_cvt_pk_bf16_f32 v84, v84, v85
	v_cvt_pk_bf16_f32 v85, v86, v87
	v_cvt_pk_bf16_f32 v86, v80, v81
	v_cvt_pk_bf16_f32 v87, v82, v83
	global_store_dwordx4 v132, v[84:87], s[98:99] offset:256
	v_add_u32_e32 v132, s20, v132
	v_cvt_pk_bf16_f32 v76, v76, v77
	v_cvt_pk_bf16_f32 v77, v78, v79
	v_cvt_pk_bf16_f32 v78, v72, v73
	v_cvt_pk_bf16_f32 v79, v74, v75
	global_store_dwordx4 v132, v[76:79], s[98:99]
	v_cvt_pk_bf16_f32 v68, v68, v69
	v_cvt_pk_bf16_f32 v69, v70, v71
	v_cvt_pk_bf16_f32 v70, v64, v65
	v_cvt_pk_bf16_f32 v71, v66, v67
	global_store_dwordx4 v132, v[68:71], s[98:99] offset:256
	v_add_u32_e32 v132, s21, v132
	v_cvt_pk_bf16_f32 v60, v60, v61
	v_cvt_pk_bf16_f32 v61, v62, v63
	v_cvt_pk_bf16_f32 v62, v56, v57
	v_cvt_pk_bf16_f32 v63, v58, v59
	global_store_dwordx4 v132, v[60:63], s[98:99]
	v_cvt_pk_bf16_f32 v52, v52, v53
	v_cvt_pk_bf16_f32 v53, v54, v55
	v_cvt_pk_bf16_f32 v54, v48, v49
	v_cvt_pk_bf16_f32 v55, v50, v51
	global_store_dwordx4 v132, v[52:55], s[98:99] offset:256
	v_add_u32_e32 v132, s20, v132
	v_cvt_pk_bf16_f32 v44, v44, v45
	v_cvt_pk_bf16_f32 v45, v46, v47
	v_cvt_pk_bf16_f32 v46, v40, v41
	v_cvt_pk_bf16_f32 v47, v42, v43
	global_store_dwordx4 v132, v[44:47], s[98:99]
	v_cvt_pk_bf16_f32 v36, v36, v37
	v_cvt_pk_bf16_f32 v37, v38, v39
	v_cvt_pk_bf16_f32 v38, v32, v33
	v_cvt_pk_bf16_f32 v39, v34, v35
	global_store_dwordx4 v132, v[36:39], s[98:99] offset:256
	v_add_u32_e32 v132, s20, v132
	v_cvt_pk_bf16_f32 v28, v28, v29
	v_cvt_pk_bf16_f32 v29, v30, v31
	v_cvt_pk_bf16_f32 v30, v24, v25
	v_cvt_pk_bf16_f32 v31, v26, v27
	global_store_dwordx4 v132, v[28:31], s[98:99]
	v_cvt_pk_bf16_f32 v20, v20, v21
	v_cvt_pk_bf16_f32 v21, v22, v23
	v_cvt_pk_bf16_f32 v22, v16, v17
	v_cvt_pk_bf16_f32 v23, v18, v19
	global_store_dwordx4 v132, v[20:23], s[98:99] offset:256
	v_add_u32_e32 v132, s20, v132
	v_cvt_pk_bf16_f32 v12, v12, v13
	v_cvt_pk_bf16_f32 v13, v14, v15
	v_cvt_pk_bf16_f32 v14, v8, v9
	v_cvt_pk_bf16_f32 v15, v10, v11
	global_store_dwordx4 v132, v[12:15], s[98:99]
	v_cvt_pk_bf16_f32 v4, v4, v5
	v_cvt_pk_bf16_f32 v5, v6, v7
	v_cvt_pk_bf16_f32 v6, v0, v1
	v_cvt_pk_bf16_f32 v7, v2, v3
	global_store_dwordx4 v132, v[4:7], s[98:99] offset:256
	s_nop 1
	v_writelane_b32 v255, 1, 62
	s_branch .LBB0_837
.Lepi_relu2:
	v_or_b32_e32 v130, s78, v179
	v_lshl_add_u32 v130, s83, 8, v130
	s_lshl_b32 s20, s66, 8
	v_lshl_or_b32 v131, v178, 3, s20
	v_or_b32_e32 v131, s79, v131
	v_mul_lo_u32 v132, v130, s88
	v_add_lshl_u32 v132, v132, v131, 1
	s_lshl_b32 s20, s88, 5
	s_mul_i32 s21, s88, 0xa0
	s_mov_b64 s[98:99], s[90:91]
	v_lshlrev_b32_e32 v133, 2, v130
	global_load_dword v188, v133, s[96:97]
	global_load_dword v189, v133, s[96:97] offset:64
	global_load_dword v190, v133, s[96:97] offset:128
	global_load_dword v191, v133, s[96:97] offset:192
	global_load_dword v192, v133, s[96:97] offset:512
	global_load_dword v193, v133, s[96:97] offset:576
	global_load_dword v194, v133, s[96:97] offset:640
	global_load_dword v195, v133, s[96:97] offset:704
	s_waitcnt vmcnt(0)
	v_mov_b32_e32 v112, v188
	v_pk_mul_f32 v[126:127], v[126:127], v[112:113] op_sel_hi:[1,0]
	v_pk_mul_f32 v[128:129], v[128:129], v[112:113] op_sel_hi:[1,0]
	v_pk_mul_f32 v[122:123], v[122:123], v[112:113] op_sel_hi:[1,0]
	v_pk_mul_f32 v[124:125], v[124:125], v[112:113] op_sel_hi:[1,0]
	v_max_f32_e32 v126, 0, v126
	v_max_f32_e32 v127, 0, v127
	v_max_f32_e32 v128, 0, v128
	v_max_f32_e32 v129, 0, v129
	v_max_f32_e32 v122, 0, v122
	v_max_f32_e32 v123, 0, v123
	v_max_f32_e32 v124, 0, v124
	v_max_f32_e32 v125, 0, v125
	v_pk_mul_f32 v[126:127], v[126:127], v[126:127]
	v_pk_mul_f32 v[128:129], v[128:129], v[128:129]
	v_pk_mul_f32 v[122:123], v[122:123], v[122:123]
	v_pk_mul_f32 v[124:125], v[124:125], v[124:125]
	v_cvt_pk_bf16_f32 v126, v126, v127
	v_cvt_pk_bf16_f32 v127, v128, v129
	v_cvt_pk_bf16_f32 v128, v122, v123
	v_cvt_pk_bf16_f32 v129, v124, v125
	global_store_dwordx4 v132, v[126:129], s[98:99]
	v_pk_mul_f32 v[118:119], v[118:119], v[112:113] op_sel_hi:[1,0]
	v_pk_mul_f32 v[120:121], v[120:121], v[112:113] op_sel_hi:[1,0]
	v_pk_mul_f32 v[114:115], v[114:115], v[112:113] op_sel_hi:[1,0]
	v_pk_mul_f32 v[116:117], v[116:117], v[112:113] op_sel_hi:[1,0]
	v_max_f32_e32 v118, 0, v118
	v_max_f32_e32 v119, 0, v119
	v_max_f32_e32 v120, 0, v120
	v_max_f32_e32 v121, 0, v121
	v_max_f32_e32 v114, 0, v114
	v_max_f32_e32 v115, 0, v115
	v_max_f32_e32 v116, 0, v116
	v_max_f32_e32 v117, 0, v117
	v_pk_mul_f32 v[118:119], v[118:119], v[118:119]
	v_pk_mul_f32 v[120:121], v[120:121], v[120:121]
	v_pk_mul_f32 v[114:115], v[114:115], v[114:115]
	v_pk_mul_f32 v[116:117], v[116:117], v[116:117]
; DI u32x4 pack8(f32x4 a, f32x4 b) { u32x4 w; w.x = cvtpk(a.x, a.y); w.y = cvtpk(a.z, a.w); w.z = cvtpk(b.x, b.y); w.w = cvtpk(b.z, b.w); return w; }
;   template <int MODE> DI void store8(int row, int col, f32x4 v0, f32x4 v1, int part) const {
;     if (MODE == EM_QKV || MODE == EM_RELU2 || MODE == EM_F32) { const float r_ = rs[row]; v0 *= r_; v1 *= r_; }
;     if (MODE == EM_TAIL) {
;       if (part >= 16) *(u32x4*)(O2 + ((size_t)(part - 16) * 1024 + (row - NPR)) * 2048 + col) = pack8(v0, v1);
;       else *(u32x4*)(O + (size_t)row * ldc + col) = pack8(v0, v1);
;     } else if (MODE == EM_SPLIT) {
;       bf16* d = (part & 1) ? O2 : O; *(u32x4*)(d + (size_t)row * ldc + col) = pack8(v0, v1);
;       if (part & 2) *(u32x4*)(O2 + (size_t)row * ldc + col) = (u32x4){0u, 0u, 0u, 0u};
;     } else if (MODE == EM_BF16) { *(u32x4*)(O + (size_t)row * ldc + col) = pack8(v0, v1); }
;     else if (MODE == EM_RELU2) {
;       f32x4 a = __builtin_elementwise_max(v0, (f32x4){0.f, 0.f, 0.f, 0.f}), b = __builtin_elementwise_max(v1, (f32x4){0.f, 0.f, 0.f, 0.f});
;       *(u32x4*)(O + (size_t)row * ldc + col) = pack8(a * a, b * b); }
	v_cvt_pk_bf16_f32 v118, v118, v119
	v_cvt_pk_bf16_f32 v119, v120, v121
	v_cvt_pk_bf16_f32 v120, v114, v115
	v_cvt_pk_bf16_f32 v121, v116, v117
	global_store_dwordx4 v132, v[118:121], s[98:99] offset:256
	v_add_u32_e32 v132, s20, v132
	v_mov_b32_e32 v112, v189
	v_pk_mul_f32 v[108:109], v[108:109], v[112:113] op_sel_hi:[1,0]
	v_pk_mul_f32 v[110:111], v[110:111], v[112:113] op_sel_hi:[1,0]
	v_pk_mul_f32 v[104:105], v[104:105], v[112:113] op_sel_hi:[1,0]
	v_pk_mul_f32 v[106:107], v[106:107], v[112:113] op_sel_hi:[1,0]
	v_max_f32_e32 v108, 0, v108
	v_max_f32_e32 v109, 0, v109
	v_max_f32_e32 v110, 0, v110
	v_max_f32_e32 v111, 0, v111
	v_max_f32_e32 v104, 0, v104
	v_max_f32_e32 v105, 0, v105
	v_max_f32_e32 v106, 0, v106
	v_max_f32_e32 v107, 0, v107
	v_pk_mul_f32 v[108:109], v[108:109], v[108:109]
	v_pk_mul_f32 v[110:111], v[110:111], v[110:111]
	v_pk_mul_f32 v[104:105], v[104:105], v[104:105]
	v_pk_mul_f32 v[106:107], v[106:107], v[106:107]
	v_cvt_pk_bf16_f32 v108, v108, v109
	v_cvt_pk_bf16_f32 v109, v110, v111
	v_cvt_pk_bf16_f32 v110, v104, v105
	v_cvt_pk_bf16_f32 v111, v106, v107
	global_store_dwordx4 v132, v[108:111], s[98:99]
	v_pk_mul_f32 v[100:101], v[100:101], v[112:113] op_sel_hi:[1,0]
	v_pk_mul_f32 v[102:103], v[102:103], v[112:113] op_sel_hi:[1,0]
	v_pk_mul_f32 v[96:97], v[96:97], v[112:113] op_sel_hi:[1,0]
	v_pk_mul_f32 v[98:99], v[98:99], v[112:113] op_sel_hi:[1,0]
	v_max_f32_e32 v100, 0, v100
	v_max_f32_e32 v101, 0, v101
	v_max_f32_e32 v102, 0, v102
	v_max_f32_e32 v103, 0, v103
	v_max_f32_e32 v96, 0, v96
	v_max_f32_e32 v97, 0, v97
	v_max_f32_e32 v98, 0, v98
	v_max_f32_e32 v99, 0, v99
	v_pk_mul_f32 v[100:101], v[100:101], v[100:101]
	v_pk_mul_f32 v[102:103], v[102:103], v[102:103]
	v_pk_mul_f32 v[96:97], v[96:97], v[96:97]
	v_pk_mul_f32 v[98:99], v[98:99], v[98:99]
	v_cvt_pk_bf16_f32 v100, v100, v101
	v_cvt_pk_bf16_f32 v101, v102, v103
	v_cvt_pk_bf16_f32 v102, v96, v97
	v_cvt_pk_bf16_f32 v103, v98, v99
	global_store_dwordx4 v132, v[100:103], s[98:99] offset:256
	v_add_u32_e32 v132, s20, v132
	v_mov_b32_e32 v112, v190
	v_pk_mul_f32 v[92:93], v[92:93], v[112:113] op_sel_hi:[1,0]
	v_pk_mul_f32 v[94:95], v[94:95], v[112:113] op_sel_hi:[1,0]
	v_pk_mul_f32 v[88:89], v[88:89], v[112:113] op_sel_hi:[1,0]
	v_pk_mul_f32 v[90:91], v[90:91], v[112:113] op_sel_hi:[1,0]
	v_max_f32_e32 v92, 0, v92
	v_max_f32_e32 v93, 0, v93
	v_max_f32_e32 v94, 0, v94
	v_max_f32_e32 v95, 0, v95
	v_max_f32_e32 v88, 0, v88
	v_max_f32_e32 v89, 0, v89
	v_max_f32_e32 v90, 0, v90
	v_max_f32_e32 v91, 0, v91
	v_pk_mul_f32 v[92:93], v[92:93], v[92:93]
	v_pk_mul_f32 v[94:95], v[94:95], v[94:95]
	v_pk_mul_f32 v[88:89], v[88:89], v[88:89]
	v_pk_mul_f32 v[90:91], v[90:91], v[90:91]
	v_cvt_pk_bf16_f32 v92, v92, v93
	v_cvt_pk_bf16_f32 v93, v94, v95
	v_cvt_pk_bf16_f32 v94, v88, v89
	v_cvt_pk_bf16_f32 v95, v90, v91
	global_store_dwordx4 v132, v[92:95], s[98:99]
	v_pk_mul_f32 v[84:85], v[84:85], v[112:113] op_sel_hi:[1,0]
	v_pk_mul_f32 v[86:87], v[86:87], v[112:113] op_sel_hi:[1,0]
	v_pk_mul_f32 v[80:81], v[80:81], v[112:113] op_sel_hi:[1,0]
	v_pk_mul_f32 v[82:83], v[82:83], v[112:113] op_sel_hi:[1,0]
	v_max_f32_e32 v84, 0, v84
	v_max_f32_e32 v85, 0, v85
	v_max_f32_e32 v86, 0, v86
	v_max_f32_e32 v87, 0, v87
	v_max_f32_e32 v80, 0, v80
	v_max_f32_e32 v81, 0, v81
	v_max_f32_e32 v82, 0, v82
	v_max_f32_e32 v83, 0, v83
	v_pk_mul_f32 v[84:85], v[84:85], v[84:85]
	v_pk_mul_f32 v[86:87], v[86:87], v[86:87]
	v_pk_mul_f32 v[80:81], v[80:81], v[80:81]
	v_pk_mul_f32 v[82:83], v[82:83], v[82:83]
	v_cvt_pk_bf16_f32 v84, v84, v85
	v_cvt_pk_bf16_f32 v85, v86, v87
	v_cvt_pk_bf16_f32 v86, v80, v81
	v_cvt_pk_bf16_f32 v87, v82, v83
	global_store_dwordx4 v132, v[84:87], s[98:99] offset:256
	v_add_u32_e32 v132, s20, v132
	v_mov_b32_e32 v112, v191
	v_pk_mul_f32 v[76:77], v[76:77], v[112:113] op_sel_hi:[1,0]
	v_pk_mul_f32 v[78:79], v[78:79], v[112:113] op_sel_hi:[1,0]
	v_pk_mul_f32 v[72:73], v[72:73], v[112:113] op_sel_hi:[1,0]
	v_pk_mul_f32 v[74:75], v[74:75], v[112:113] op_sel_hi:[1,0]
	v_max_f32_e32 v76, 0, v76
	v_max_f32_e32 v77, 0, v77
	v_max_f32_e32 v78, 0, v78
	v_max_f32_e32 v79, 0, v79
	v_max_f32_e32 v72, 0, v72
	v_max_f32_e32 v73, 0, v73
	v_max_f32_e32 v74, 0, v74
	v_max_f32_e32 v75, 0, v75
	v_pk_mul_f32 v[76:77], v[76:77], v[76:77]
	v_pk_mul_f32 v[78:79], v[78:79], v[78:79]
	v_pk_mul_f32 v[72:73], v[72:73], v[72:73]
	v_pk_mul_f32 v[74:75], v[74:75], v[74:75]
	v_cvt_pk_bf16_f32 v76, v76, v77
	v_cvt_pk_bf16_f32 v77, v78, v79
	v_cvt_pk_bf16_f32 v78, v72, v73
	v_cvt_pk_bf16_f32 v79, v74, v75
	global_store_dwordx4 v132, v[76:79], s[98:99]
	v_pk_mul_f32 v[68:69], v[68:69], v[112:113] op_sel_hi:[1,0]
	v_pk_mul_f32 v[70:71], v[70:71], v[112:113] op_sel_hi:[1,0]
	v_pk_mul_f32 v[64:65], v[64:65], v[112:113] op_sel_hi:[1,0]
	v_pk_mul_f32 v[66:67], v[66:67], v[112:113] op_sel_hi:[1,0]
	v_max_f32_e32 v68, 0, v68
	v_max_f32_e32 v69, 0, v69
	v_max_f32_e32 v70, 0, v70
	v_max_f32_e32 v71, 0, v71
	v_max_f32_e32 v64, 0, v64
	v_max_f32_e32 v65, 0, v65
	v_max_f32_e32 v66, 0, v66
	v_max_f32_e32 v67, 0, v67
	v_pk_mul_f32 v[68:69], v[68:69], v[68:69]
	v_pk_mul_f32 v[70:71], v[70:71], v[70:71]
	v_pk_mul_f32 v[64:65], v[64:65], v[64:65]
	v_pk_mul_f32 v[66:67], v[66:67], v[66:67]
	v_cvt_pk_bf16_f32 v68, v68, v69
	v_cvt_pk_bf16_f32 v69, v70, v71
	v_cvt_pk_bf16_f32 v70, v64, v65
	v_cvt_pk_bf16_f32 v71, v66, v67
	global_store_dwordx4 v132, v[68:71], s[98:99] offset:256
	v_add_u32_e32 v132, s21, v132
	v_mov_b32_e32 v112, v192
	v_pk_mul_f32 v[60:61], v[60:61], v[112:113] op_sel_hi:[1,0]
	v_pk_mul_f32 v[62:63], v[62:63], v[112:113] op_sel_hi:[1,0]
	v_pk_mul_f32 v[56:57], v[56:57], v[112:113] op_sel_hi:[1,0]
; DI u32x4 pack8(f32x4 a, f32x4 b) { u32x4 w; w.x = cvtpk(a.x, a.y); w.y = cvtpk(a.z, a.w); w.z = cvtpk(b.x, b.y); w.w = cvtpk(b.z, b.w); return w; }
;   template <int MODE> DI void store8(int row, int col, f32x4 v0, f32x4 v1, int part) const {
;     if (MODE == EM_QKV || MODE == EM_RELU2 || MODE == EM_F32) { const float r_ = rs[row]; v0 *= r_; v1 *= r_; }
;     if (MODE == EM_TAIL) {
;       if (part >= 16) *(u32x4*)(O2 + ((size_t)(part - 16) * 1024 + (row - NPR)) * 2048 + col) = pack8(v0, v1);
;       else *(u32x4*)(O + (size_t)row * ldc + col) = pack8(v0, v1);
;     } else if (MODE == EM_SPLIT) {
;       bf16* d = (part & 1) ? O2 : O; *(u32x4*)(d + (size_t)row * ldc + col) = pack8(v0, v1);
;       if (part & 2) *(u32x4*)(O2 + (size_t)row * ldc + col) = (u32x4){0u, 0u, 0u, 0u};
;     } else if (MODE == EM_BF16) { *(u32x4*)(O + (size_t)row * ldc + col) = pack8(v0, v1); }
;     else if (MODE == EM_RELU2) {
;       f32x4 a = __builtin_elementwise_max(v0, (f32x4){0.f, 0.f, 0.f, 0.f}), b = __builtin_elementwise_max(v1, (f32x4){0.f, 0.f, 0.f, 0.f});
;       *(u32x4*)(O + (size_t)row * ldc + col) = pack8(a * a, b * b); }
	v_pk_mul_f32 v[58:59], v[58:59], v[112:113] op_sel_hi:[1,0]
	v_max_f32_e32 v60, 0, v60
	v_max_f32_e32 v61, 0, v61
	v_max_f32_e32 v62, 0, v62
	v_max_f32_e32 v63, 0, v63
	v_max_f32_e32 v56, 0, v56
	v_max_f32_e32 v57, 0, v57
	v_max_f32_e32 v58, 0, v58
	v_max_f32_e32 v59, 0, v59
	v_pk_mul_f32 v[60:61], v[60:61], v[60:61]
	v_pk_mul_f32 v[62:63], v[62:63], v[62:63]
	v_pk_mul_f32 v[56:57], v[56:57], v[56:57]
	v_pk_mul_f32 v[58:59], v[58:59], v[58:59]
	v_cvt_pk_bf16_f32 v60, v60, v61
	v_cvt_pk_bf16_f32 v61, v62, v63
	v_cvt_pk_bf16_f32 v62, v56, v57
	v_cvt_pk_bf16_f32 v63, v58, v59
	global_store_dwordx4 v132, v[60:63], s[98:99]
	v_pk_mul_f32 v[52:53], v[52:53], v[112:113] op_sel_hi:[1,0]
	v_pk_mul_f32 v[54:55], v[54:55], v[112:113] op_sel_hi:[1,0]
	v_pk_mul_f32 v[48:49], v[48:49], v[112:113] op_sel_hi:[1,0]
	v_pk_mul_f32 v[50:51], v[50:51], v[112:113] op_sel_hi:[1,0]
	v_max_f32_e32 v52, 0, v52
	v_max_f32_e32 v53, 0, v53
	v_max_f32_e32 v54, 0, v54
	v_max_f32_e32 v55, 0, v55
	v_max_f32_e32 v48, 0, v48
	v_max_f32_e32 v49, 0, v49
	v_max_f32_e32 v50, 0, v50
	v_max_f32_e32 v51, 0, v51
	v_pk_mul_f32 v[52:53], v[52:53], v[52:53]
	v_pk_mul_f32 v[54:55], v[54:55], v[54:55]
	v_pk_mul_f32 v[48:49], v[48:49], v[48:49]
	v_pk_mul_f32 v[50:51], v[50:51], v[50:51]
	v_cvt_pk_bf16_f32 v52, v52, v53
	v_cvt_pk_bf16_f32 v53, v54, v55
	v_cvt_pk_bf16_f32 v54, v48, v49
	v_cvt_pk_bf16_f32 v55, v50, v51
	global_store_dwordx4 v132, v[52:55], s[98:99] offset:256
	v_add_u32_e32 v132, s20, v132
	v_mov_b32_e32 v112, v193
	v_pk_mul_f32 v[44:45], v[44:45], v[112:113] op_sel_hi:[1,0]
	v_pk_mul_f32 v[46:47], v[46:47], v[112:113] op_sel_hi:[1,0]
	v_pk_mul_f32 v[40:41], v[40:41], v[112:113] op_sel_hi:[1,0]
	v_pk_mul_f32 v[42:43], v[42:43], v[112:113] op_sel_hi:[1,0]
	v_max_f32_e32 v44, 0, v44
	v_max_f32_e32 v45, 0, v45
	v_max_f32_e32 v46, 0, v46
	v_max_f32_e32 v47, 0, v47
	v_max_f32_e32 v40, 0, v40
	v_max_f32_e32 v41, 0, v41
	v_max_f32_e32 v42, 0, v42
	v_max_f32_e32 v43, 0, v43
	v_pk_mul_f32 v[44:45], v[44:45], v[44:45]
	v_pk_mul_f32 v[46:47], v[46:47], v[46:47]
	v_pk_mul_f32 v[40:41], v[40:41], v[40:41]
	v_pk_mul_f32 v[42:43], v[42:43], v[42:43]
	v_cvt_pk_bf16_f32 v44, v44, v45
	v_cvt_pk_bf16_f32 v45, v46, v47
	v_cvt_pk_bf16_f32 v46, v40, v41
	v_cvt_pk_bf16_f32 v47, v42, v43
	global_store_dwordx4 v132, v[44:47], s[98:99]
	v_pk_mul_f32 v[36:37], v[36:37], v[112:113] op_sel_hi:[1,0]
	v_pk_mul_f32 v[38:39], v[38:39], v[112:113] op_sel_hi:[1,0]
	v_pk_mul_f32 v[32:33], v[32:33], v[112:113] op_sel_hi:[1,0]
	v_pk_mul_f32 v[34:35], v[34:35], v[112:113] op_sel_hi:[1,0]
	v_max_f32_e32 v36, 0, v36
	v_max_f32_e32 v37, 0, v37
	v_max_f32_e32 v38, 0, v38
	v_max_f32_e32 v39, 0, v39
	v_max_f32_e32 v32, 0, v32
	v_max_f32_e32 v33, 0, v33
	v_max_f32_e32 v34, 0, v34
	v_max_f32_e32 v35, 0, v35
	v_pk_mul_f32 v[36:37], v[36:37], v[36:37]
	v_pk_mul_f32 v[38:39], v[38:39], v[38:39]
	v_pk_mul_f32 v[32:33], v[32:33], v[32:33]
	v_pk_mul_f32 v[34:35], v[34:35], v[34:35]
	v_cvt_pk_bf16_f32 v36, v36, v37
	v_cvt_pk_bf16_f32 v37, v38, v39
	v_cvt_pk_bf16_f32 v38, v32, v33
	v_cvt_pk_bf16_f32 v39, v34, v35
	global_store_dwordx4 v132, v[36:39], s[98:99] offset:256
	v_add_u32_e32 v132, s20, v132
	v_mov_b32_e32 v112, v194
	v_pk_mul_f32 v[28:29], v[28:29], v[112:113] op_sel_hi:[1,0]
	v_pk_mul_f32 v[30:31], v[30:31], v[112:113] op_sel_hi:[1,0]
	v_pk_mul_f32 v[24:25], v[24:25], v[112:113] op_sel_hi:[1,0]
	v_pk_mul_f32 v[26:27], v[26:27], v[112:113] op_sel_hi:[1,0]
	v_max_f32_e32 v28, 0, v28
	v_max_f32_e32 v29, 0, v29
	v_max_f32_e32 v30, 0, v30
	v_max_f32_e32 v31, 0, v31
	v_max_f32_e32 v24, 0, v24
	v_max_f32_e32 v25, 0, v25
	v_max_f32_e32 v26, 0, v26
	v_max_f32_e32 v27, 0, v27
	v_pk_mul_f32 v[28:29], v[28:29], v[28:29]
	v_pk_mul_f32 v[30:31], v[30:31], v[30:31]
	v_pk_mul_f32 v[24:25], v[24:25], v[24:25]
	v_pk_mul_f32 v[26:27], v[26:27], v[26:27]
	v_cvt_pk_bf16_f32 v28, v28, v29
	v_cvt_pk_bf16_f32 v29, v30, v31
	v_cvt_pk_bf16_f32 v30, v24, v25
	v_cvt_pk_bf16_f32 v31, v26, v27
	global_store_dwordx4 v132, v[28:31], s[98:99]
	v_pk_mul_f32 v[20:21], v[20:21], v[112:113] op_sel_hi:[1,0]
	v_pk_mul_f32 v[22:23], v[22:23], v[112:113] op_sel_hi:[1,0]
	v_pk_mul_f32 v[16:17], v[16:17], v[112:113] op_sel_hi:[1,0]
	v_pk_mul_f32 v[18:19], v[18:19], v[112:113] op_sel_hi:[1,0]
	v_max_f32_e32 v20, 0, v20
	v_max_f32_e32 v21, 0, v21
	v_max_f32_e32 v22, 0, v22
	v_max_f32_e32 v23, 0, v23
	v_max_f32_e32 v16, 0, v16
	v_max_f32_e32 v17, 0, v17
	v_max_f32_e32 v18, 0, v18
	v_max_f32_e32 v19, 0, v19
	v_pk_mul_f32 v[20:21], v[20:21], v[20:21]
	v_pk_mul_f32 v[22:23], v[22:23], v[22:23]
	v_pk_mul_f32 v[16:17], v[16:17], v[16:17]
	v_pk_mul_f32 v[18:19], v[18:19], v[18:19]
	v_cvt_pk_bf16_f32 v20, v20, v21
	v_cvt_pk_bf16_f32 v21, v22, v23
	v_cvt_pk_bf16_f32 v22, v16, v17
	v_cvt_pk_bf16_f32 v23, v18, v19
	global_store_dwordx4 v132, v[20:23], s[98:99] offset:256
	v_add_u32_e32 v132, s20, v132
	v_mov_b32_e32 v112, v195
	v_pk_mul_f32 v[12:13], v[12:13], v[112:113] op_sel_hi:[1,0]
	v_pk_mul_f32 v[14:15], v[14:15], v[112:113] op_sel_hi:[1,0]
	v_pk_mul_f32 v[8:9], v[8:9], v[112:113] op_sel_hi:[1,0]
	v_pk_mul_f32 v[10:11], v[10:11], v[112:113] op_sel_hi:[1,0]
	v_max_f32_e32 v12, 0, v12
	v_max_f32_e32 v13, 0, v13
	v_max_f32_e32 v14, 0, v14
	v_max_f32_e32 v15, 0, v15
	v_max_f32_e32 v8, 0, v8
	v_max_f32_e32 v9, 0, v9
	v_max_f32_e32 v10, 0, v10
	v_max_f32_e32 v11, 0, v11
	v_pk_mul_f32 v[12:13], v[12:13], v[12:13]
	v_pk_mul_f32 v[14:15], v[14:15], v[14:15]
	v_pk_mul_f32 v[8:9], v[8:9], v[8:9]
	v_pk_mul_f32 v[10:11], v[10:11], v[10:11]
	v_cvt_pk_bf16_f32 v12, v12, v13
	v_cvt_pk_bf16_f32 v13, v14, v15
	v_cvt_pk_bf16_f32 v14, v8, v9
	v_cvt_pk_bf16_f32 v15, v10, v11
	global_store_dwordx4 v132, v[12:15], s[98:99]
	v_pk_mul_f32 v[4:5], v[4:5], v[112:113] op_sel_hi:[1,0]
	v_pk_mul_f32 v[6:7], v[6:7], v[112:113] op_sel_hi:[1,0]
	v_pk_mul_f32 v[0:1], v[0:1], v[112:113] op_sel_hi:[1,0]
	v_pk_mul_f32 v[2:3], v[2:3], v[112:113] op_sel_hi:[1,0]
	v_max_f32_e32 v4, 0, v4
	v_max_f32_e32 v5, 0, v5
	v_max_f32_e32 v6, 0, v6
	v_max_f32_e32 v7, 0, v7
	v_max_f32_e32 v0, 0, v0
	v_max_f32_e32 v1, 0, v1
	v_max_f32_e32 v2, 0, v2
	v_max_f32_e32 v3, 0, v3
	v_pk_mul_f32 v[4:5], v[4:5], v[4:5]
	v_pk_mul_f32 v[6:7], v[6:7], v[6:7]
	v_pk_mul_f32 v[0:1], v[0:1], v[0:1]
	v_pk_mul_f32 v[2:3], v[2:3], v[2:3]
	v_cvt_pk_bf16_f32 v4, v4, v5
	v_cvt_pk_bf16_f32 v5, v6, v7
	v_cvt_pk_bf16_f32 v6, v0, v1
	v_cvt_pk_bf16_f32 v7, v2, v3
	global_store_dwordx4 v132, v[4:7], s[98:99] offset:256
	s_nop 1
	v_writelane_b32 v255, 1, 62
	s_branch .LBB0_837
